# attention unit epilogue: 16 z-gate loads hoisted before the end-of-unit barrier into idle regs, g_sub staged in idle K ring buffer and read with ds_read, store ladder waits only lgkmcnt
# speedup vs baseline: 1.0118x; 1.0118x over previous
.LBB0_737:
	v_mov_b32_e32 v130, v210
	s_add_i32 s74, s74, 1
	v_ashrrev_i32_e32 v189, 31, v188
	v_lshl_add_u64 v[128:129], v[188:189], 0, s[46:47]
	v_lshlrev_b32_e32 v130, 2, v130
	v_lshlrev_b64 v[140:141], 11, v[128:129]
	v_lshl_or_b32 v140, s75, 1, v140
	v_ashrrev_i32_e32 v131, 31, v130
	v_lshl_add_u64 v[128:129], s[48:49], 0, v[140:141]
	v_lshlrev_b64 v[136:137], 1, v[130:131]
	v_lshl_add_u64 v[134:135], v[128:129], 0, v[136:137]
	v_lshlrev_b32_e32 v215, 3, v206
	global_load_dwordx2 v[204:205], v215, s[52:53]
	global_load_dwordx2 v[160:161], v[134:135], off
	global_load_dwordx2 v[162:163], v[134:135], off offset:16
	global_load_dwordx2 v[164:165], v[134:135], off offset:32
	global_load_dwordx2 v[166:167], v[134:135], off offset:48
	global_load_dwordx2 v[168:169], v[134:135], off offset:64
	global_load_dwordx2 v[170:171], v[134:135], off offset:80
	global_load_dwordx2 v[172:173], v[134:135], off offset:96
	global_load_dwordx2 v[174:175], v[134:135], off offset:112
	global_load_dwordx2 v[202:203], v[134:135], off offset:128
	global_load_dwordx2 v[244:245], v[134:135], off offset:160
	global_load_dwordx2 v[246:247], v[134:135], off offset:176
	global_load_dwordx2 v[248:249], v[134:135], off offset:192
	global_load_dwordx2 v[250:251], v[134:135], off offset:208
	global_load_dwordx2 v[252:253], v[134:135], off offset:224
	global_load_dwordx2 v[254:255], v[134:135], off offset:240
	s_lshr_b32 s0, s87, 2
	s_add_i32 s0, s0, 0x8000
	v_add_u32_e32 v217, s0, v215
	v_lshl_add_u32 v219, v210, 4, s0
	s_waitcnt lgkmcnt(0)
	s_barrier
	s_waitcnt vmcnt(15)
	ds_write_b64 v217, v[204:205]
	global_load_dwordx2 v[204:205], v[134:135], off offset:144
	v_mov_b32_e32 v128, v197
	v_mov_b32_e32 v129, v196
	s_nop 0
	v_permlane32_swap_b32_e32 v197, v128
	v_permlane32_swap_b32_e32 v196, v129
	v_add_f32_e32 v148, v197, v128
	v_add_f32_e32 v149, v196, v129
	v_div_scale_f32 v150, s[0:1], v148, v148, 1.0
	v_div_scale_f32 v152, s[0:1], v149, v149, -v208
	v_rcp_f32_e32 v154, v150
	v_rcp_f32_e32 v155, v152
	v_div_scale_f32 v151, vcc, 1.0, v148, 1.0
	v_fma_f32 v156, -v150, v154, 1.0
	v_fma_f32 v157, -v152, v155, 1.0
	v_fmac_f32_e32 v154, v156, v154
	v_div_scale_f32 v153, s[36:37], -v208, v149, -v208
	v_fmac_f32_e32 v155, v157, v155
	v_mul_f32_e32 v156, v151, v154
	v_mul_f32_e32 v157, v153, v155
	v_fma_f32 v158, -v150, v156, v151
	v_fma_f32 v159, -v152, v157, v153
	v_fmac_f32_e32 v156, v158, v154
	v_fmac_f32_e32 v157, v159, v155
	v_fma_f32 v150, -v150, v156, v151
	v_fma_f32 v151, -v152, v157, v153
	v_div_fmas_f32 v150, v150, v154, v156
	s_mov_b64 vcc, s[36:37]
	v_div_fixup_f32 v148, v150, v148, 1.0
	v_div_fmas_f32 v150, v151, v155, v157
	v_div_fixup_f32 v150, v150, v149, -v208
	v_pk_mul_f32 v[96:97], v[96:97], v[150:151] op_sel_hi:[1,0]
	v_pk_mul_f32 v[98:99], v[98:99], v[150:151] op_sel_hi:[1,0]
	v_pk_fma_f32 v[112:113], v[112:113], v[148:149], v[96:97] op_sel_hi:[1,0,1]
	v_pk_fma_f32 v[114:115], v[114:115], v[148:149], v[98:99] op_sel_hi:[1,0,1]
	v_mul_f32_e32 v96, v113, v113
	v_pk_fma_f32 v[96:97], v[112:113], v[112:113], v[96:97] op_sel_hi:[1,1,0]
	v_pk_mul_f32 v[100:101], v[100:101], v[150:151] op_sel_hi:[1,0]
	v_mul_f32_e32 v98, v115, v115
	v_pk_fma_f32 v[96:97], v[114:115], v[114:115], v[96:97]
	v_pk_fma_f32 v[100:101], v[116:117], v[148:149], v[100:101] op_sel_hi:[1,0,1]
	v_pk_add_f32 v[96:97], v[98:99], v[96:97] op_sel_hi:[0,1]
	v_pk_mul_f32 v[102:103], v[102:103], v[150:151] op_sel_hi:[1,0]
	v_mul_f32_e32 v116, v101, v101
	v_pk_fma_f32 v[96:97], v[100:101], v[100:101], v[96:97]
	v_pk_fma_f32 v[102:103], v[118:119], v[148:149], v[102:103] op_sel_hi:[1,0,1]
	v_pk_add_f32 v[96:97], v[116:117], v[96:97] op_sel_hi:[0,1]
	v_pk_mul_f32 v[104:105], v[104:105], v[150:151] op_sel_hi:[1,0]
	v_mul_f32_e32 v118, v103, v103
	v_pk_fma_f32 v[96:97], v[102:103], v[102:103], v[96:97]
	v_pk_fma_f32 v[104:105], v[120:121], v[148:149], v[104:105] op_sel_hi:[1,0,1]
	v_pk_add_f32 v[96:97], v[118:119], v[96:97] op_sel_hi:[0,1]
	v_pk_mul_f32 v[106:107], v[106:107], v[150:151] op_sel_hi:[1,0]
	v_mul_f32_e32 v120, v105, v105
	v_pk_fma_f32 v[96:97], v[104:105], v[104:105], v[96:97]
	v_pk_fma_f32 v[106:107], v[122:123], v[148:149], v[106:107] op_sel_hi:[1,0,1]
	v_pk_add_f32 v[96:97], v[120:121], v[96:97] op_sel_hi:[0,1]
	v_pk_mul_f32 v[108:109], v[108:109], v[150:151] op_sel_hi:[1,0]
	v_mul_f32_e32 v122, v107, v107
	v_pk_fma_f32 v[96:97], v[106:107], v[106:107], v[96:97]
	v_pk_fma_f32 v[108:109], v[124:125], v[148:149], v[108:109] op_sel_hi:[1,0,1]
	v_pk_add_f32 v[96:97], v[122:123], v[96:97] op_sel_hi:[0,1]
	v_pk_mul_f32 v[110:111], v[110:111], v[150:151] op_sel_hi:[1,0]
	v_pk_fma_f32 v[96:97], v[108:109], v[108:109], v[96:97]
	v_mul_f32_e32 v98, v109, v109
	v_pk_fma_f32 v[110:111], v[126:127], v[148:149], v[110:111] op_sel_hi:[1,0,1]
	v_pk_add_f32 v[96:97], v[98:99], v[96:97] op_sel_hi:[0,1]
	v_pk_fma_f32 v[96:97], v[110:111], v[110:111], v[96:97]
	v_mul_f32_e32 v98, v111, v111
	v_pk_mul_f32 v[82:83], v[82:83], v[150:151] op_sel_hi:[1,0]
	v_pk_add_f32 v[118:119], v[98:99], v[96:97] op_sel_hi:[0,1]
	v_pk_fma_f32 v[96:97], v[66:67], v[148:149], v[82:83] op_sel_hi:[1,0,1]
	v_pk_mul_f32 v[66:67], v[80:81], v[150:151] op_sel_hi:[1,0]
	v_lshl_add_u64 v[132:133], v[130:131], 2, s[52:53]
	v_pk_fma_f32 v[98:99], v[64:65], v[148:149], v[66:67] op_sel_hi:[1,0,1]
	v_pk_fma_f32 v[64:65], v[98:99], v[98:99], v[118:119]
	v_mul_f32_e32 v66, v99, v99
	ds_read_b128 v[128:131], v219
	v_pk_add_f32 v[64:65], v[66:67], v[64:65] op_sel_hi:[0,1]
	v_pk_fma_f32 v[64:65], v[96:97], v[96:97], v[64:65]
	v_mul_f32_e32 v66, v97, v97
	v_pk_add_f32 v[64:65], v[66:67], v[64:65] op_sel_hi:[0,1]
	v_pk_mul_f32 v[66:67], v[86:87], v[150:151] op_sel_hi:[1,0]
	v_pk_mul_f32 v[50:51], v[50:51], v[150:151] op_sel_hi:[1,0]
	v_pk_fma_f32 v[80:81], v[70:71], v[148:149], v[66:67] op_sel_hi:[1,0,1]
	v_pk_mul_f32 v[66:67], v[84:85], v[150:151] op_sel_hi:[1,0]
	v_pk_mul_f32 v[18:19], v[18:19], v[150:151] op_sel_hi:[1,0]
	v_pk_fma_f32 v[82:83], v[68:69], v[148:149], v[66:67] op_sel_hi:[1,0,1]
	s_mov_b32 s0, 0x800000
	v_pk_fma_f32 v[64:65], v[82:83], v[82:83], v[64:65]
	v_mul_f32_e32 v66, v83, v83
	v_pk_add_f32 v[64:65], v[66:67], v[64:65] op_sel_hi:[0,1]
	v_pk_fma_f32 v[64:65], v[80:81], v[80:81], v[64:65]
	v_mul_f32_e32 v66, v81, v81
	v_pk_add_f32 v[64:65], v[66:67], v[64:65] op_sel_hi:[0,1]
	v_pk_mul_f32 v[66:67], v[90:91], v[150:151] op_sel_hi:[1,0]
	v_lshl_add_u64 v[140:141], s[68:69], 0, v[140:141]
	v_pk_fma_f32 v[74:75], v[74:75], v[148:149], v[66:67] op_sel_hi:[1,0,1]
	v_pk_mul_f32 v[66:67], v[88:89], v[150:151] op_sel_hi:[1,0]
	v_pk_fma_f32 v[72:73], v[72:73], v[148:149], v[66:67] op_sel_hi:[1,0,1]
	s_cmp_eq_u32 s74, 4
	v_pk_fma_f32 v[64:65], v[72:73], v[72:73], v[64:65]
	v_mul_f32_e32 v66, v73, v73
	v_pk_add_f32 v[64:65], v[66:67], v[64:65] op_sel_hi:[0,1]
	v_pk_fma_f32 v[64:65], v[74:75], v[74:75], v[64:65]
	v_mul_f32_e32 v66, v75, v75
	v_pk_add_f32 v[64:65], v[66:67], v[64:65] op_sel_hi:[0,1]
	v_pk_mul_f32 v[66:67], v[94:95], v[150:151] op_sel_hi:[1,0]
	s_waitcnt vmcnt(0) lgkmcnt(0)
	v_lshlrev_b32_e32 v116, 16, v160
	v_pk_fma_f32 v[68:69], v[78:79], v[148:149], v[66:67] op_sel_hi:[1,0,1]
	v_pk_mul_f32 v[66:67], v[92:93], v[150:151] op_sel_hi:[1,0]
	v_and_b32_e32 v117, 0xffff0000, v160
	v_pk_fma_f32 v[70:71], v[76:77], v[148:149], v[66:67] op_sel_hi:[1,0,1]
	s_nop 0
	v_pk_fma_f32 v[64:65], v[70:71], v[70:71], v[64:65]
	v_mul_f32_e32 v66, v71, v71
	v_pk_add_f32 v[64:65], v[66:67], v[64:65] op_sel_hi:[0,1]
	v_pk_fma_f32 v[64:65], v[68:69], v[68:69], v[64:65]
	v_mul_f32_e32 v66, v69, v69
	v_pk_add_f32 v[76:77], v[66:67], v[64:65] op_sel_hi:[0,1]
	v_pk_fma_f32 v[64:65], v[34:35], v[148:149], v[50:51] op_sel_hi:[1,0,1]
	v_pk_mul_f32 v[34:35], v[48:49], v[150:151] op_sel_hi:[1,0]
	s_nop 0
	v_pk_fma_f32 v[66:67], v[32:33], v[148:149], v[34:35] op_sel_hi:[1,0,1]
	s_nop 0
	v_pk_fma_f32 v[32:33], v[66:67], v[66:67], v[76:77]
	v_mul_f32_e32 v34, v67, v67
	v_pk_add_f32 v[32:33], v[34:35], v[32:33] op_sel_hi:[0,1]
	v_pk_fma_f32 v[32:33], v[64:65], v[64:65], v[32:33]
	v_mul_f32_e32 v34, v65, v65
	v_pk_add_f32 v[32:33], v[34:35], v[32:33] op_sel_hi:[0,1]
	v_pk_mul_f32 v[34:35], v[54:55], v[150:151] op_sel_hi:[1,0]
	s_nop 0
	v_pk_fma_f32 v[48:49], v[38:39], v[148:149], v[34:35] op_sel_hi:[1,0,1]
	v_pk_mul_f32 v[34:35], v[52:53], v[150:151] op_sel_hi:[1,0]
	s_nop 0
	v_pk_fma_f32 v[50:51], v[36:37], v[148:149], v[34:35] op_sel_hi:[1,0,1]
	s_nop 0
	v_pk_fma_f32 v[32:33], v[50:51], v[50:51], v[32:33]
	v_mul_f32_e32 v34, v51, v51
	v_pk_add_f32 v[32:33], v[34:35], v[32:33] op_sel_hi:[0,1]
	v_pk_fma_f32 v[32:33], v[48:49], v[48:49], v[32:33]
	v_mul_f32_e32 v34, v49, v49
	v_pk_add_f32 v[32:33], v[34:35], v[32:33] op_sel_hi:[0,1]
	v_pk_mul_f32 v[34:35], v[58:59], v[150:151] op_sel_hi:[1,0]
	s_nop 0
	v_pk_fma_f32 v[42:43], v[42:43], v[148:149], v[34:35] op_sel_hi:[1,0,1]
	v_pk_mul_f32 v[34:35], v[56:57], v[150:151] op_sel_hi:[1,0]
	s_nop 0
	v_pk_fma_f32 v[40:41], v[40:41], v[148:149], v[34:35] op_sel_hi:[1,0,1]
	s_nop 0
	v_pk_fma_f32 v[32:33], v[40:41], v[40:41], v[32:33]
	v_mul_f32_e32 v34, v41, v41
	v_pk_add_f32 v[32:33], v[34:35], v[32:33] op_sel_hi:[0,1]
	v_pk_fma_f32 v[32:33], v[42:43], v[42:43], v[32:33]
	v_mul_f32_e32 v34, v43, v43
	v_pk_add_f32 v[32:33], v[34:35], v[32:33] op_sel_hi:[0,1]
	v_pk_mul_f32 v[34:35], v[62:63], v[150:151] op_sel_hi:[1,0]
	s_nop 0
	v_pk_fma_f32 v[36:37], v[46:47], v[148:149], v[34:35] op_sel_hi:[1,0,1]
	v_pk_mul_f32 v[34:35], v[60:61], v[150:151] op_sel_hi:[1,0]
	s_nop 0
	v_pk_fma_f32 v[38:39], v[44:45], v[148:149], v[34:35] op_sel_hi:[1,0,1]
	s_nop 0
	v_pk_fma_f32 v[32:33], v[38:39], v[38:39], v[32:33]
	v_mul_f32_e32 v34, v39, v39
	v_pk_add_f32 v[32:33], v[34:35], v[32:33] op_sel_hi:[0,1]
	v_pk_fma_f32 v[32:33], v[36:37], v[36:37], v[32:33]
	v_mul_f32_e32 v34, v37, v37
	v_pk_add_f32 v[44:45], v[34:35], v[32:33] op_sel_hi:[0,1]
	v_pk_fma_f32 v[32:33], v[2:3], v[148:149], v[18:19] op_sel_hi:[1,0,1]
	v_pk_mul_f32 v[2:3], v[16:17], v[150:151] op_sel_hi:[1,0]
	s_nop 0
	v_pk_fma_f32 v[34:35], v[0:1], v[148:149], v[2:3] op_sel_hi:[1,0,1]
	s_nop 0
	v_pk_fma_f32 v[0:1], v[34:35], v[34:35], v[44:45]
	v_mul_f32_e32 v2, v35, v35
	v_pk_add_f32 v[0:1], v[2:3], v[0:1] op_sel_hi:[0,1]
	v_pk_fma_f32 v[0:1], v[32:33], v[32:33], v[0:1]
	v_mul_f32_e32 v2, v33, v33
	v_pk_add_f32 v[0:1], v[2:3], v[0:1] op_sel_hi:[0,1]
	v_pk_mul_f32 v[2:3], v[22:23], v[150:151] op_sel_hi:[1,0]
	v_lshlrev_b32_e32 v22, 16, v165
	v_pk_fma_f32 v[16:17], v[6:7], v[148:149], v[2:3] op_sel_hi:[1,0,1]
	v_pk_mul_f32 v[2:3], v[20:21], v[150:151] op_sel_hi:[1,0]
	v_and_b32_e32 v23, 0xffff0000, v165
	v_pk_fma_f32 v[18:19], v[4:5], v[148:149], v[2:3] op_sel_hi:[1,0,1]
	s_nop 0
	v_pk_fma_f32 v[0:1], v[18:19], v[18:19], v[0:1]
	v_mul_f32_e32 v2, v19, v19
	v_pk_add_f32 v[0:1], v[2:3], v[0:1] op_sel_hi:[0,1]
	v_pk_fma_f32 v[0:1], v[16:17], v[16:17], v[0:1]
	v_mul_f32_e32 v2, v17, v17
	v_pk_add_f32 v[0:1], v[2:3], v[0:1] op_sel_hi:[0,1]
	v_pk_mul_f32 v[2:3], v[26:27], v[150:151] op_sel_hi:[1,0]
	s_nop 0
	v_pk_fma_f32 v[10:11], v[10:11], v[148:149], v[2:3] op_sel_hi:[1,0,1]
	v_pk_mul_f32 v[2:3], v[24:25], v[150:151] op_sel_hi:[1,0]
	s_nop 0
	v_pk_fma_f32 v[8:9], v[8:9], v[148:149], v[2:3] op_sel_hi:[1,0,1]
	s_nop 0
	v_pk_fma_f32 v[0:1], v[8:9], v[8:9], v[0:1]
	v_mul_f32_e32 v2, v9, v9
	v_pk_add_f32 v[0:1], v[2:3], v[0:1] op_sel_hi:[0,1]
	v_pk_fma_f32 v[0:1], v[10:11], v[10:11], v[0:1]
	v_mul_f32_e32 v2, v11, v11
	v_pk_add_f32 v[4:5], v[2:3], v[0:1] op_sel_hi:[0,1]
	v_pk_mul_f32 v[2:3], v[28:29], v[150:151] op_sel_hi:[1,0]
	v_pk_mul_f32 v[0:1], v[30:31], v[150:151] op_sel_hi:[1,0]
	v_pk_fma_f32 v[2:3], v[12:13], v[148:149], v[2:3] op_sel_hi:[1,0,1]
	v_pk_fma_f32 v[0:1], v[14:15], v[148:149], v[0:1] op_sel_hi:[1,0,1]
	v_pk_fma_f32 v[4:5], v[2:3], v[2:3], v[4:5]
	v_mul_f32_e32 v6, v3, v3
	v_pk_add_f32 v[4:5], v[6:7], v[4:5] op_sel_hi:[0,1]
	v_pk_fma_f32 v[4:5], v[0:1], v[0:1], v[4:5]
	v_mul_f32_e32 v6, v1, v1
	v_pk_add_f32 v[4:5], v[6:7], v[4:5] op_sel_hi:[0,1]
	v_mov_b32_e32 v5, v4
	s_nop 1
	v_permlane32_swap_b32_e32 v4, v5
	v_add_f32_e32 v4, v4, v5
	v_fmamk_f32 v4, v4, 0x3c000000, v232
	v_mul_f32_e32 v5, 0x4b800000, v4
	v_cmp_gt_f32_e32 vcc, s0, v4
	v_lshlrev_b32_e32 v12, 16, v161
	v_and_b32_e32 v13, 0xffff0000, v161
	v_cndmask_b32_e32 v4, v4, v5, vcc
	v_rsq_f32_e32 v6, v4
	v_lshl_add_u64 v[4:5], v[140:141], 0, v[136:137]
	v_mul_f32_e32 v7, 0x45800000, v6
	v_cndmask_b32_e32 v6, v6, v7, vcc
	v_mul_f32_e32 v6, 0x3f077f5a, v6
	v_pk_mul_f32 v[14:15], v[112:113], v[6:7] op_sel_hi:[1,0]
	v_pk_mul_f32 v[20:21], v[114:115], v[6:7] op_sel_hi:[1,0]
	v_pk_mul_f32 v[14:15], v[128:129], v[14:15]
	v_pk_mul_f32 v[20:21], v[130:131], v[20:21]
	v_pk_mul_f32 v[14:15], v[14:15], v[116:117]
	v_pk_mul_f32 v[12:13], v[20:21], v[12:13]
	v_cvt_pk_bf16_f32 v14, v14, v15
	v_cvt_pk_bf16_f32 v15, v12, v13
	global_store_dwordx2 v[4:5], v[14:15], off
	ds_read_b128 v[12:15], v219 offset:32
	v_pk_mul_f32 v[20:21], v[100:101], v[6:7] op_sel_hi:[1,0]
	v_pk_mul_f32 v[24:25], v[104:105], v[6:7] op_sel_hi:[1,0]
	v_pk_mul_f32 v[26:27], v[106:107], v[6:7] op_sel_hi:[1,0]
	v_pk_mul_f32 v[28:29], v[110:111], v[6:7] op_sel_hi:[1,0]
	v_pk_mul_f32 v[30:31], v[98:99], v[6:7] op_sel_hi:[1,0]
	v_pk_mul_f32 v[44:45], v[96:97], v[6:7] op_sel_hi:[1,0]
	v_pk_mul_f32 v[32:33], v[32:33], v[6:7] op_sel_hi:[1,0]
	v_pk_mul_f32 v[18:19], v[18:19], v[6:7] op_sel_hi:[1,0]
	v_pk_mul_f32 v[16:17], v[16:17], v[6:7] op_sel_hi:[1,0]
	v_pk_mul_f32 v[8:9], v[8:9], v[6:7] op_sel_hi:[1,0]
	v_pk_mul_f32 v[10:11], v[10:11], v[6:7] op_sel_hi:[1,0]
	v_pk_mul_f32 v[2:3], v[2:3], v[6:7] op_sel_hi:[1,0]
	v_pk_mul_f32 v[0:1], v[0:1], v[6:7] op_sel_hi:[1,0]
	s_waitcnt lgkmcnt(0)
	v_pk_mul_f32 v[12:13], v[12:13], v[20:21]
	v_lshlrev_b32_e32 v20, 16, v162
	v_and_b32_e32 v21, 0xffff0000, v162
	v_pk_mul_f32 v[12:13], v[12:13], v[20:21]
	v_pk_mul_f32 v[20:21], v[102:103], v[6:7] op_sel_hi:[1,0]
	v_cvt_pk_bf16_f32 v12, v12, v13
	v_pk_mul_f32 v[14:15], v[14:15], v[20:21]
	v_lshlrev_b32_e32 v20, 16, v163
	v_and_b32_e32 v21, 0xffff0000, v163
	v_pk_mul_f32 v[14:15], v[14:15], v[20:21]
	v_lshlrev_b32_e32 v20, 16, v164
	v_cvt_pk_bf16_f32 v13, v14, v15
	global_store_dwordx2 v[4:5], v[12:13], off offset:16
	ds_read_b128 v[12:15], v219 offset:64
	v_and_b32_e32 v21, 0xffff0000, v164
	s_waitcnt lgkmcnt(0)
	v_pk_mul_f32 v[12:13], v[12:13], v[24:25]
	v_pk_mul_f32 v[14:15], v[14:15], v[26:27]
	v_pk_mul_f32 v[12:13], v[12:13], v[20:21]
	v_pk_mul_f32 v[14:15], v[14:15], v[22:23]
	v_cvt_pk_bf16_f32 v12, v12, v13
	v_cvt_pk_bf16_f32 v13, v14, v15
	global_store_dwordx2 v[4:5], v[12:13], off offset:32
	ds_read_b128 v[12:15], v219 offset:96
	s_nop 0
	v_pk_mul_f32 v[26:27], v[108:109], v[6:7] op_sel_hi:[1,0]
	v_lshlrev_b32_e32 v22, 16, v166
	v_and_b32_e32 v23, 0xffff0000, v166
	v_lshlrev_b32_e32 v24, 16, v167
	v_and_b32_e32 v25, 0xffff0000, v167
	s_waitcnt lgkmcnt(0)
	v_pk_mul_f32 v[12:13], v[12:13], v[26:27]
	v_pk_mul_f32 v[14:15], v[14:15], v[28:29]
	v_pk_mul_f32 v[12:13], v[12:13], v[22:23]
	v_pk_mul_f32 v[14:15], v[14:15], v[24:25]
	v_cvt_pk_bf16_f32 v12, v12, v13
	v_cvt_pk_bf16_f32 v13, v14, v15
	global_store_dwordx2 v[4:5], v[12:13], off offset:48
	ds_read_b128 v[12:15], v219 offset:128
	s_nop 0
	v_lshlrev_b32_e32 v28, 16, v168
	v_and_b32_e32 v29, 0xffff0000, v168
	v_lshlrev_b32_e32 v20, 16, v169
	v_and_b32_e32 v21, 0xffff0000, v169
	s_waitcnt lgkmcnt(0)
	v_pk_mul_f32 v[12:13], v[30:31], v[12:13]
	v_pk_mul_f32 v[14:15], v[44:45], v[14:15]
	v_pk_mul_f32 v[12:13], v[12:13], v[28:29]
	v_pk_mul_f32 v[14:15], v[14:15], v[20:21]
	v_cvt_pk_bf16_f32 v12, v12, v13
	v_cvt_pk_bf16_f32 v13, v14, v15
	global_store_dwordx2 v[4:5], v[12:13], off offset:64
	ds_read_b128 v[12:15], v219 offset:160
	v_pk_mul_f32 v[28:29], v[82:83], v[6:7] op_sel_hi:[1,0]
	v_pk_mul_f32 v[30:31], v[80:81], v[6:7] op_sel_hi:[1,0]
	v_lshlrev_b32_e32 v20, 16, v170
	v_and_b32_e32 v21, 0xffff0000, v170
	v_lshlrev_b32_e32 v22, 16, v171
	v_and_b32_e32 v23, 0xffff0000, v171
	v_pk_mul_f32 v[44:45], v[64:65], v[6:7] op_sel_hi:[1,0]
	s_waitcnt lgkmcnt(0)
	v_pk_mul_f32 v[12:13], v[28:29], v[12:13]
	v_pk_mul_f32 v[14:15], v[30:31], v[14:15]
	v_pk_mul_f32 v[12:13], v[12:13], v[20:21]
	v_pk_mul_f32 v[14:15], v[14:15], v[22:23]
	v_cvt_pk_bf16_f32 v12, v12, v13
	v_cvt_pk_bf16_f32 v13, v14, v15
	global_store_dwordx2 v[4:5], v[12:13], off offset:80
	ds_read_b128 v[12:15], v219 offset:192
	v_lshlrev_b32_e32 v20, 16, v172
	v_and_b32_e32 v21, 0xffff0000, v172
	v_lshlrev_b32_e32 v22, 16, v173
	v_and_b32_e32 v23, 0xffff0000, v173
	v_pk_mul_f32 v[24:25], v[72:73], v[6:7] op_sel_hi:[1,0]
	v_pk_mul_f32 v[28:29], v[74:75], v[6:7] op_sel_hi:[1,0]
	v_pk_mul_f32 v[30:31], v[66:67], v[6:7] op_sel_hi:[1,0]
	s_waitcnt lgkmcnt(0)
	v_pk_mul_f32 v[12:13], v[24:25], v[12:13]
	v_pk_mul_f32 v[14:15], v[28:29], v[14:15]
	v_pk_mul_f32 v[12:13], v[12:13], v[20:21]
	v_pk_mul_f32 v[14:15], v[14:15], v[22:23]
	v_cvt_pk_bf16_f32 v12, v12, v13
	v_cvt_pk_bf16_f32 v13, v14, v15
	global_store_dwordx2 v[4:5], v[12:13], off offset:96
	ds_read_b128 v[12:15], v219 offset:224
	s_nop 0
	v_lshlrev_b32_e32 v22, 16, v174
	v_and_b32_e32 v23, 0xffff0000, v174
	v_lshlrev_b32_e32 v24, 16, v175
	v_and_b32_e32 v25, 0xffff0000, v175
	v_pk_mul_f32 v[26:27], v[70:71], v[6:7] op_sel_hi:[1,0]
	v_pk_mul_f32 v[28:29], v[68:69], v[6:7] op_sel_hi:[1,0]
	s_waitcnt lgkmcnt(0)
	v_pk_mul_f32 v[12:13], v[26:27], v[12:13]
	v_pk_mul_f32 v[14:15], v[28:29], v[14:15]
	v_pk_mul_f32 v[12:13], v[12:13], v[22:23]
	v_pk_mul_f32 v[14:15], v[14:15], v[24:25]
	v_cvt_pk_bf16_f32 v12, v12, v13
	v_cvt_pk_bf16_f32 v13, v14, v15
	global_store_dwordx2 v[4:5], v[12:13], off offset:112
	ds_read_b128 v[12:15], v219 offset:256
	s_nop 0
	v_lshlrev_b32_e32 v28, 16, v202
	v_and_b32_e32 v29, 0xffff0000, v202
	v_lshlrev_b32_e32 v20, 16, v203
	v_and_b32_e32 v21, 0xffff0000, v203
	s_waitcnt lgkmcnt(0)
	v_pk_mul_f32 v[12:13], v[30:31], v[12:13]
	v_pk_mul_f32 v[14:15], v[44:45], v[14:15]
	v_pk_mul_f32 v[12:13], v[12:13], v[28:29]
	v_pk_mul_f32 v[14:15], v[14:15], v[20:21]
	v_cvt_pk_bf16_f32 v12, v12, v13
	v_cvt_pk_bf16_f32 v13, v14, v15
	global_store_dwordx2 v[4:5], v[12:13], off offset:128
	ds_read_b128 v[12:15], v219 offset:288
	v_pk_mul_f32 v[28:29], v[50:51], v[6:7] op_sel_hi:[1,0]
	v_pk_mul_f32 v[30:31], v[48:49], v[6:7] op_sel_hi:[1,0]
	v_lshlrev_b32_e32 v20, 16, v204
	v_and_b32_e32 v21, 0xffff0000, v204
	v_lshlrev_b32_e32 v22, 16, v205
	v_and_b32_e32 v23, 0xffff0000, v205
	s_waitcnt lgkmcnt(0)
	v_pk_mul_f32 v[12:13], v[28:29], v[12:13]
	v_pk_mul_f32 v[14:15], v[30:31], v[14:15]
	v_pk_mul_f32 v[12:13], v[12:13], v[20:21]
	v_pk_mul_f32 v[14:15], v[14:15], v[22:23]
	v_cvt_pk_bf16_f32 v12, v12, v13
	v_cvt_pk_bf16_f32 v13, v14, v15
	global_store_dwordx2 v[4:5], v[12:13], off offset:144
	ds_read_b128 v[12:15], v219 offset:320
	v_lshlrev_b32_e32 v20, 16, v244
	v_and_b32_e32 v21, 0xffff0000, v244
	v_lshlrev_b32_e32 v22, 16, v245
	v_and_b32_e32 v23, 0xffff0000, v245
	v_pk_mul_f32 v[24:25], v[40:41], v[6:7] op_sel_hi:[1,0]
	v_pk_mul_f32 v[28:29], v[42:43], v[6:7] op_sel_hi:[1,0]
	v_pk_mul_f32 v[30:31], v[34:35], v[6:7] op_sel_hi:[1,0]
	s_waitcnt lgkmcnt(0)
	v_pk_mul_f32 v[12:13], v[24:25], v[12:13]
	v_pk_mul_f32 v[14:15], v[28:29], v[14:15]
	v_pk_mul_f32 v[12:13], v[12:13], v[20:21]
	v_pk_mul_f32 v[14:15], v[14:15], v[22:23]
	v_cvt_pk_bf16_f32 v12, v12, v13
	v_cvt_pk_bf16_f32 v13, v14, v15
	global_store_dwordx2 v[4:5], v[12:13], off offset:160
	ds_read_b128 v[12:15], v219 offset:352
	s_nop 0
	v_lshlrev_b32_e32 v22, 16, v246
	v_and_b32_e32 v23, 0xffff0000, v246
	v_lshlrev_b32_e32 v24, 16, v247
	v_and_b32_e32 v25, 0xffff0000, v247
	v_pk_mul_f32 v[26:27], v[38:39], v[6:7] op_sel_hi:[1,0]
	v_pk_mul_f32 v[28:29], v[36:37], v[6:7] op_sel_hi:[1,0]
	s_waitcnt lgkmcnt(0)
	v_pk_mul_f32 v[12:13], v[26:27], v[12:13]
	v_pk_mul_f32 v[14:15], v[28:29], v[14:15]
	v_pk_mul_f32 v[12:13], v[12:13], v[22:23]
	v_pk_mul_f32 v[14:15], v[14:15], v[24:25]
	v_cvt_pk_bf16_f32 v12, v12, v13
	v_cvt_pk_bf16_f32 v13, v14, v15
	global_store_dwordx2 v[4:5], v[12:13], off offset:176
	ds_read_b128 v[12:15], v219 offset:384
	s_nop 0
	v_lshlrev_b32_e32 v28, 16, v248
	v_and_b32_e32 v29, 0xffff0000, v248
	v_lshlrev_b32_e32 v20, 16, v249
	v_and_b32_e32 v21, 0xffff0000, v249
	s_waitcnt lgkmcnt(0)
	v_pk_mul_f32 v[12:13], v[30:31], v[12:13]
	v_pk_mul_f32 v[14:15], v[32:33], v[14:15]
	v_pk_mul_f32 v[12:13], v[12:13], v[28:29]
	v_pk_mul_f32 v[14:15], v[14:15], v[20:21]
	v_cvt_pk_bf16_f32 v12, v12, v13
	v_cvt_pk_bf16_f32 v13, v14, v15
	global_store_dwordx2 v[4:5], v[12:13], off offset:192
	ds_read_b128 v[12:15], v219 offset:416
	v_lshlrev_b32_e32 v20, 16, v250
	v_and_b32_e32 v21, 0xffff0000, v250
	v_lshlrev_b32_e32 v22, 16, v251
	v_and_b32_e32 v23, 0xffff0000, v251
	s_waitcnt lgkmcnt(0)
	v_pk_mul_f32 v[12:13], v[18:19], v[12:13]
	v_pk_mul_f32 v[14:15], v[16:17], v[14:15]
	v_pk_mul_f32 v[12:13], v[12:13], v[20:21]
	v_pk_mul_f32 v[14:15], v[14:15], v[22:23]
	v_cvt_pk_bf16_f32 v12, v12, v13
	v_cvt_pk_bf16_f32 v13, v14, v15
	global_store_dwordx2 v[4:5], v[12:13], off offset:208
	ds_read_b128 v[12:15], v219 offset:448
	v_lshlrev_b32_e32 v16, 16, v252
	v_and_b32_e32 v17, 0xffff0000, v252
	v_lshlrev_b32_e32 v18, 16, v253
	v_and_b32_e32 v19, 0xffff0000, v253
	s_waitcnt lgkmcnt(0)
	v_pk_mul_f32 v[8:9], v[8:9], v[12:13]
	v_pk_mul_f32 v[10:11], v[10:11], v[14:15]
	v_pk_mul_f32 v[8:9], v[8:9], v[16:17]
	v_pk_mul_f32 v[10:11], v[10:11], v[18:19]
	v_cvt_pk_bf16_f32 v8, v8, v9
	v_cvt_pk_bf16_f32 v9, v10, v11
	global_store_dwordx2 v[4:5], v[8:9], off offset:224
	ds_read_b128 v[8:11], v219 offset:480
	v_lshlrev_b32_e32 v12, 16, v254
	v_and_b32_e32 v13, 0xffff0000, v254
	v_lshlrev_b32_e32 v14, 16, v255
	v_and_b32_e32 v15, 0xffff0000, v255
	s_waitcnt lgkmcnt(0)
	v_pk_mul_f32 v[2:3], v[2:3], v[8:9]
	v_pk_mul_f32 v[0:1], v[0:1], v[10:11]
	v_pk_mul_f32 v[2:3], v[2:3], v[12:13]
	v_pk_mul_f32 v[0:1], v[0:1], v[14:15]
	v_cvt_pk_bf16_f32 v2, v2, v3
	v_cvt_pk_bf16_f32 v3, v0, v1
	global_store_dwordx2 v[4:5], v[2:3], off offset:240
	s_cbranch_scc1 .LBB0_735
